# mixer C neighbourhood tiles: bias words of a key-row tile loaded at once and masked by select instead of 32 exec-masked serial LDS round trips; its softmax with scalar fma/add
# speedup vs baseline: 1.0486x; 1.0089x over previous
.LBB0_224:
	s_and_saveexec_b64 s[46:47], s[42:43]
	s_cbranch_execz .LBB0_294
	s_bitcmp1_b32 s70, 0
	s_cselect_b32 s42, 0x4600, 0
	v_or_b32_e32 v0, s42, v204
	v_add_u32_e32 v0, v0, v205
	ds_read_b128 v[2:5], v0
	ds_read_b128 v[6:9], v0 offset:4608
	s_setprio 1
	ds_read_b128 v[10:13], v0 offset:32
	ds_read_b128 v[176:179], v0 offset:4640
	s_waitcnt vmcnt(3) lgkmcnt(3)
	v_mfma_f32_32x32x16_bf16 v[64:79], v[2:5], v[80:83], 0
	s_waitcnt lgkmcnt(2)
	v_mfma_f32_32x32x16_bf16 v[48:63], v[6:9], v[80:83], 0
	ds_read_b128 v[2:5], v0 offset:64
	ds_read_b128 v[6:9], v0 offset:4672
	s_waitcnt vmcnt(2) lgkmcnt(3)
	v_mfma_f32_32x32x16_bf16 v[64:79], v[10:13], v[84:87], v[64:79]
	s_waitcnt lgkmcnt(2)
	v_mfma_f32_32x32x16_bf16 v[48:63], v[176:179], v[84:87], v[48:63]
	ds_read_b128 v[10:13], v0 offset:96
	ds_read_b128 v[176:179], v0 offset:4704
	s_waitcnt vmcnt(1) lgkmcnt(3)
	v_mfma_f32_32x32x16_bf16 v[64:79], v[2:5], v[88:91], v[64:79]
	s_waitcnt lgkmcnt(2)
	v_mfma_f32_32x32x16_bf16 v[48:63], v[6:9], v[88:91], v[48:63]
	s_waitcnt vmcnt(0) lgkmcnt(1)
	v_mfma_f32_32x32x16_bf16 v[64:79], v[10:13], v[92:95], v[64:79]
	s_waitcnt lgkmcnt(0)
	v_mfma_f32_32x32x16_bf16 v[48:63], v[176:179], v[92:95], v[48:63]
	v_or_b32_e32 v0, s42, v112
	v_add_u32_e32 v0, v0, v232
	v_add_u32_e32 v155, 0x2000, v0
	v_add_u32_e32 v0, 0x3000, v0
	ds_read2_b64 v[2:5], v155 offset0:128 offset1:130
	ds_read2_b64 v[6:9], v0 offset0:160 offset1:162
	s_mov_b64 s[42:43], -1
	s_and_b64 vcc, exec, s[64:65]
	s_nop 2
	v_mov_b32_e32 v201, v63
	v_mov_b32_e32 v200, v62
	v_mov_b32_e32 v199, v61
	v_mov_b32_e32 v198, v60
	v_mov_b32_e32 v197, v59
	v_mov_b32_e32 v196, v58
	v_mov_b32_e32 v195, v57
	v_mov_b32_e32 v194, v56
	v_mov_b32_e32 v193, v55
	v_mov_b32_e32 v192, v54
	v_mov_b32_e32 v191, v53
	v_mov_b32_e32 v190, v52
	v_mov_b32_e32 v189, v51
	v_mov_b32_e32 v188, v50
	v_mov_b32_e32 v187, v49
	v_mov_b32_e32 v186, v48
	v_mov_b32_e32 v185, v79
	v_mov_b32_e32 v184, v78
	v_mov_b32_e32 v183, v77
	v_mov_b32_e32 v182, v76
	v_mov_b32_e32 v181, v75
	v_mov_b32_e32 v180, v74
	v_mov_b32_e32 v179, v73
	v_mov_b32_e32 v178, v72
	v_mov_b32_e32 v177, v71
	v_mov_b32_e32 v176, v70
	v_mov_b32_e32 v15, v69
	v_mov_b32_e32 v14, v68
	v_mov_b32_e32 v13, v67
	v_mov_b32_e32 v12, v66
	v_mov_b32_e32 v11, v65
	v_mov_b32_e32 v10, v64
	s_cbranch_vccz .LBB0_296
	s_add_i32 s42, s67, s70
	v_cmp_ge_i32_e32 vcc, s42, v145
	v_cmp_lt_i32_e64 s[42:43], s42, v149
	v_mov_b32_e32 v218, 0xff800000
	ds_read2_b32 v[10:11], v153 offset0:0 offset1:1
	ds_read2_b32 v[12:13], v153 offset0:2 offset1:3
	ds_read2_b32 v[14:15], v153 offset0:8 offset1:9
	ds_read2_b32 v[176:177], v153 offset0:10 offset1:11
	ds_read2_b32 v[178:179], v153 offset0:16 offset1:17
	ds_read2_b32 v[180:181], v153 offset0:18 offset1:19
	ds_read2_b32 v[182:183], v153 offset0:24 offset1:25
	ds_read2_b32 v[184:185], v153 offset0:26 offset1:27
	ds_read2_b32 v[186:187], v153 offset0:32 offset1:33
	ds_read2_b32 v[188:189], v153 offset0:34 offset1:35
	ds_read2_b32 v[190:191], v153 offset0:40 offset1:41
	ds_read2_b32 v[192:193], v153 offset0:42 offset1:43
	ds_read2_b32 v[194:195], v153 offset0:48 offset1:49
	ds_read2_b32 v[196:197], v153 offset0:50 offset1:51
	ds_read2_b32 v[198:199], v153 offset0:56 offset1:57
	ds_read2_b32 v[200:201], v153 offset0:58 offset1:59
	s_waitcnt lgkmcnt(0)
	v_fmac_f32_e32 v10, 0x3e38aa3b, v64
	v_fmac_f32_e32 v11, 0x3e38aa3b, v65
	v_fmac_f32_e32 v12, 0x3e38aa3b, v66
	v_fmac_f32_e32 v13, 0x3e38aa3b, v67
	v_fmac_f32_e32 v14, 0x3e38aa3b, v68
	v_fmac_f32_e32 v15, 0x3e38aa3b, v69
	v_fmac_f32_e32 v176, 0x3e38aa3b, v70
	v_fmac_f32_e32 v177, 0x3e38aa3b, v71
	v_fmac_f32_e32 v178, 0x3e38aa3b, v72
	v_fmac_f32_e32 v179, 0x3e38aa3b, v73
	v_fmac_f32_e32 v180, 0x3e38aa3b, v74
	v_fmac_f32_e32 v181, 0x3e38aa3b, v75
	v_fmac_f32_e32 v182, 0x3e38aa3b, v76
	v_fmac_f32_e32 v183, 0x3e38aa3b, v77
	v_fmac_f32_e32 v184, 0x3e38aa3b, v78
	v_fmac_f32_e32 v185, 0x3e38aa3b, v79
	v_fmac_f32_e32 v186, 0x3e38aa3b, v48
	v_fmac_f32_e32 v187, 0x3e38aa3b, v49
	v_fmac_f32_e32 v188, 0x3e38aa3b, v50
	v_fmac_f32_e32 v189, 0x3e38aa3b, v51
	v_fmac_f32_e32 v190, 0x3e38aa3b, v52
	v_fmac_f32_e32 v191, 0x3e38aa3b, v53
	v_fmac_f32_e32 v192, 0x3e38aa3b, v54
	v_fmac_f32_e32 v193, 0x3e38aa3b, v55
	v_fmac_f32_e32 v194, 0x3e38aa3b, v56
	v_fmac_f32_e32 v195, 0x3e38aa3b, v57
	v_fmac_f32_e32 v196, 0x3e38aa3b, v58
	v_fmac_f32_e32 v197, 0x3e38aa3b, v59
	v_fmac_f32_e32 v198, 0x3e38aa3b, v60
	v_fmac_f32_e32 v199, 0x3e38aa3b, v61
	v_fmac_f32_e32 v200, 0x3e38aa3b, v62
	v_fmac_f32_e32 v201, 0x3e38aa3b, v63
	v_readlane_b32 s64, v254, 24
	s_and_b64 s[42:43], vcc, s[42:43]
	v_readlane_b32 s65, v254, 25
	s_and_b64 s[74:75], s[42:43], s[64:65]
	v_cndmask_b32_e64 v10, v218, v10, s[74:75]
	v_readlane_b32 s64, v254, 26
	v_readlane_b32 s65, v254, 27
	s_and_b64 s[74:75], s[42:43], s[64:65]
	v_cndmask_b32_e64 v11, v218, v11, s[74:75]
	v_readlane_b32 s64, v254, 28
	v_readlane_b32 s65, v254, 29
	s_and_b64 s[74:75], s[42:43], s[64:65]
	v_cndmask_b32_e64 v12, v218, v12, s[74:75]
	v_readlane_b32 s64, v254, 30
	v_readlane_b32 s65, v254, 31
	s_and_b64 s[74:75], s[42:43], s[64:65]
	v_cndmask_b32_e64 v13, v218, v13, s[74:75]
	v_readlane_b32 s64, v254, 32
	v_readlane_b32 s65, v254, 33
	s_and_b64 s[74:75], s[42:43], s[64:65]
	v_cndmask_b32_e64 v14, v218, v14, s[74:75]
	v_readlane_b32 s64, v254, 34
	v_readlane_b32 s65, v254, 35
	s_and_b64 s[74:75], s[42:43], s[64:65]
	v_cndmask_b32_e64 v15, v218, v15, s[74:75]
	v_readlane_b32 s64, v254, 36
	v_readlane_b32 s65, v254, 37
	s_and_b64 s[74:75], s[42:43], s[64:65]
	v_cndmask_b32_e64 v176, v218, v176, s[74:75]
	v_readlane_b32 s64, v254, 38
	v_readlane_b32 s65, v254, 39
	s_and_b64 s[74:75], s[42:43], s[64:65]
	v_cndmask_b32_e64 v177, v218, v177, s[74:75]
	v_readlane_b32 s64, v254, 40
	v_readlane_b32 s65, v254, 41
	v_readlane_b32 s74, v254, 42
	s_and_b64 s[64:65], s[42:43], s[64:65]
	v_readlane_b32 s75, v254, 43
	s_and_b64 s[74:75], s[64:65], s[74:75]
	v_cndmask_b32_e64 v178, v218, v178, s[74:75]
	v_readlane_b32 s64, v254, 44
	v_readlane_b32 s65, v254, 45
	v_readlane_b32 s74, v254, 46
	s_and_b64 s[64:65], s[42:43], s[64:65]
	v_readlane_b32 s75, v254, 47
	s_and_b64 s[74:75], s[64:65], s[74:75]
	v_cndmask_b32_e64 v179, v218, v179, s[74:75]
	v_readlane_b32 s64, v254, 48
	v_readlane_b32 s65, v254, 49
	v_readlane_b32 s74, v254, 50
	s_and_b64 s[64:65], s[42:43], s[64:65]
	v_readlane_b32 s75, v254, 51
	s_and_b64 s[74:75], s[64:65], s[74:75]
	v_cndmask_b32_e64 v180, v218, v180, s[74:75]
	v_readlane_b32 s64, v254, 52
	v_readlane_b32 s65, v254, 53
	v_readlane_b32 s74, v254, 54
	s_and_b64 s[64:65], s[42:43], s[64:65]
	v_readlane_b32 s75, v254, 55
	s_and_b64 s[74:75], s[64:65], s[74:75]
	v_cndmask_b32_e64 v181, v218, v181, s[74:75]
	v_readlane_b32 s64, v254, 56
	v_readlane_b32 s65, v254, 57
	v_readlane_b32 s74, v254, 58
	s_and_b64 s[64:65], s[42:43], s[64:65]
	v_readlane_b32 s75, v254, 59
	s_and_b64 s[74:75], s[64:65], s[74:75]
	v_cndmask_b32_e64 v182, v218, v182, s[74:75]
	v_readlane_b32 s64, v254, 60
	v_readlane_b32 s65, v254, 61
	v_readlane_b32 s74, v254, 62
	s_and_b64 s[64:65], s[42:43], s[64:65]
	v_readlane_b32 s75, v254, 63
	s_and_b64 s[74:75], s[64:65], s[74:75]
	v_cndmask_b32_e64 v183, v218, v183, s[74:75]
	v_readlane_b32 s64, v255, 0
	v_readlane_b32 s65, v255, 1
	v_readlane_b32 s74, v255, 2
	s_and_b64 s[64:65], s[42:43], s[64:65]
	v_readlane_b32 s75, v255, 3
	s_and_b64 s[74:75], s[64:65], s[74:75]
	v_cndmask_b32_e64 v184, v218, v184, s[74:75]
	v_readlane_b32 s64, v255, 4
	v_readlane_b32 s65, v255, 5
	v_readlane_b32 s74, v255, 6
	s_and_b64 s[64:65], s[42:43], s[64:65]
	v_readlane_b32 s75, v255, 7
	s_and_b64 s[74:75], s[64:65], s[74:75]
	v_cndmask_b32_e64 v185, v218, v185, s[74:75]
	v_readlane_b32 s64, v255, 8
	v_readlane_b32 s65, v255, 9
	v_readlane_b32 s74, v255, 10
	s_and_b64 s[64:65], s[42:43], s[64:65]
	v_readlane_b32 s75, v255, 11
	s_and_b64 s[74:75], s[64:65], s[74:75]
	v_cndmask_b32_e64 v186, v218, v186, s[74:75]
	v_readlane_b32 s64, v255, 12
	v_readlane_b32 s65, v255, 13
	s_and_b64 s[64:65], s[42:43], s[64:65]
	s_and_b64 s[74:75], s[64:65], s[94:95]
	v_cndmask_b32_e64 v187, v218, v187, s[74:75]
	s_and_b64 s[64:65], s[42:43], s[96:97]
	s_and_b64 s[74:75], s[64:65], s[40:41]
	v_cndmask_b32_e64 v188, v218, v188, s[74:75]
	s_and_b64 s[64:65], s[42:43], s[4:5]
	s_and_b64 s[74:75], s[64:65], s[6:7]
	v_cndmask_b32_e64 v189, v218, v189, s[74:75]
	s_and_b64 s[64:65], s[42:43], s[8:9]
	s_and_b64 s[74:75], s[64:65], s[10:11]
	v_cndmask_b32_e64 v190, v218, v190, s[74:75]
	s_and_b64 s[64:65], s[42:43], s[12:13]
	s_and_b64 s[74:75], s[64:65], s[14:15]
	v_cndmask_b32_e64 v191, v218, v191, s[74:75]
	s_and_b64 s[64:65], s[42:43], s[16:17]
	s_and_b64 s[74:75], s[64:65], s[18:19]
	v_cndmask_b32_e64 v192, v218, v192, s[74:75]
	s_and_b64 s[64:65], s[42:43], s[20:21]
	s_and_b64 s[74:75], s[64:65], s[22:23]
	v_cndmask_b32_e64 v193, v218, v193, s[74:75]
	s_and_b64 s[74:75], s[42:43], s[24:25]
	v_cndmask_b32_e64 v194, v218, v194, s[74:75]
	s_and_b64 s[74:75], s[42:43], s[26:27]
	v_cndmask_b32_e64 v195, v218, v195, s[74:75]
	s_and_b64 s[74:75], s[42:43], s[28:29]
	v_cndmask_b32_e64 v196, v218, v196, s[74:75]
	s_and_b64 s[74:75], s[42:43], s[30:31]
	v_cndmask_b32_e64 v197, v218, v197, s[74:75]
	s_and_b64 s[74:75], s[42:43], s[34:35]
	v_cndmask_b32_e64 v198, v218, v198, s[74:75]
	s_and_b64 s[74:75], s[42:43], s[36:37]
	v_cndmask_b32_e64 v199, v218, v199, s[74:75]
	s_and_b64 s[74:75], s[42:43], s[0:1]
	v_cndmask_b32_e64 v200, v218, v200, s[74:75]
	s_and_b64 s[64:65], s[42:43], s[38:39]
	v_cndmask_b32_e64 v201, v218, v201, s[64:65]
	s_mov_b64 s[42:43], exec
	v_max3_f32 v157, v10, s55, v11
	v_max3_f32 v157, v157, v12, v13
	v_max3_f32 v157, v157, v14, v15
	v_max3_f32 v157, v157, v176, v177
	v_max3_f32 v157, v157, v178, v179
	v_max3_f32 v157, v157, v180, v181
	v_max3_f32 v157, v157, v182, v183
	v_max3_f32 v157, v157, v184, v185
	v_max3_f32 v157, v157, v186, v187
	v_max3_f32 v157, v157, v188, v189
	v_max3_f32 v157, v157, v190, v191
	v_max3_f32 v157, v157, v192, v193
	v_max3_f32 v157, v157, v194, v195
	v_max3_f32 v157, v157, v196, v197
	v_max3_f32 v157, v157, v198, v199
	v_max3_f32 v157, v157, v200, v201
	v_mov_b32_e32 v159, v157
	s_nop 1
	v_permlane32_swap_b32_e32 v157, v159
	v_max_f32_e32 v159, v159, v159
	v_max_f32_e32 v157, v157, v157
	v_max_f32_e32 v157, v157, v159

.LBB0_293:
	v_mov_b32_e32 v48, 0x3e38aa3b
	v_cndmask_b32_e64 v48, 1.0, v48, s[48:49]
	v_fma_f32 v10, v48, v10, -v174
	v_fma_f32 v11, v48, v11, -v174
	v_exp_f32_e32 v10, v10
	v_exp_f32_e32 v11, v11
	v_fma_f32 v12, v48, v12, -v174
	v_fma_f32 v13, v48, v13, -v174
	v_add_f32_e32 v219, 0, v10
	v_add_f32_e32 v220, 0, v11
	v_exp_f32_e32 v12, v12
	v_exp_f32_e32 v13, v13
	v_fma_f32 v14, v48, v14, -v174
	v_fma_f32 v15, v48, v15, -v174
	v_add_f32_e32 v219, v12, v219
	v_add_f32_e32 v220, v13, v220
	v_exp_f32_e32 v14, v14
	v_exp_f32_e32 v15, v15
	v_fma_f32 v176, v48, v176, -v174
	v_fma_f32 v177, v48, v177, -v174
	v_add_f32_e32 v219, v14, v219
	v_add_f32_e32 v220, v15, v220
	v_exp_f32_e32 v50, v176
	v_exp_f32_e32 v51, v177
	v_fma_f32 v178, v48, v178, -v174
	v_fma_f32 v179, v48, v179, -v174
	v_add_f32_e32 v219, v50, v219
	v_add_f32_e32 v220, v51, v220
	v_exp_f32_e32 v56, v178
	v_exp_f32_e32 v57, v179
	v_fma_f32 v180, v48, v180, -v174
	v_fma_f32 v181, v48, v181, -v174
	v_add_f32_e32 v219, v56, v219
	v_add_f32_e32 v220, v57, v220
	v_exp_f32_e32 v58, v180
	v_exp_f32_e32 v59, v181
	v_fma_f32 v182, v48, v182, -v174
	v_fma_f32 v183, v48, v183, -v174
	v_add_f32_e32 v219, v58, v219
	v_add_f32_e32 v220, v59, v220
	v_exp_f32_e32 v60, v182
	v_exp_f32_e32 v61, v183
	v_fma_f32 v184, v48, v184, -v174
	v_fma_f32 v185, v48, v185, -v174
	v_add_f32_e32 v219, v60, v219
	v_add_f32_e32 v220, v61, v220
	v_exp_f32_e32 v62, v184
	v_exp_f32_e32 v63, v185
	v_fma_f32 v186, v48, v186, -v174
	v_fma_f32 v187, v48, v187, -v174
	v_add_f32_e32 v219, v62, v219
	v_add_f32_e32 v220, v63, v220
	v_exp_f32_e32 v64, v186
	v_exp_f32_e32 v65, v187
	v_fma_f32 v188, v48, v188, -v174
	v_fma_f32 v189, v48, v189, -v174
	v_add_f32_e32 v219, v64, v219
	v_add_f32_e32 v220, v65, v220
	v_exp_f32_e32 v66, v188
	v_exp_f32_e32 v67, v189
	v_fma_f32 v190, v48, v190, -v174
	v_fma_f32 v191, v48, v191, -v174
	v_add_f32_e32 v219, v66, v219
	v_add_f32_e32 v220, v67, v220
	v_exp_f32_e32 v68, v190
	v_exp_f32_e32 v69, v191
	v_fma_f32 v192, v48, v192, -v174
	v_fma_f32 v193, v48, v193, -v174
	v_add_f32_e32 v219, v68, v219
	v_add_f32_e32 v220, v69, v220
	v_exp_f32_e32 v70, v192
	v_exp_f32_e32 v71, v193
	v_fma_f32 v194, v48, v194, -v174
	v_fma_f32 v195, v48, v195, -v174
	v_add_f32_e32 v219, v70, v219
	v_add_f32_e32 v220, v71, v220
	v_exp_f32_e32 v72, v194
	v_exp_f32_e32 v73, v195
	v_fma_f32 v196, v48, v196, -v174
	v_fma_f32 v197, v48, v197, -v174
	v_add_f32_e32 v219, v72, v219
	v_add_f32_e32 v220, v73, v220
	v_exp_f32_e32 v74, v196
	v_exp_f32_e32 v75, v197
	v_fma_f32 v198, v48, v198, -v174
	v_fma_f32 v199, v48, v199, -v174
	v_add_f32_e32 v219, v74, v219
	v_add_f32_e32 v220, v75, v220
	v_exp_f32_e32 v76, v198
	v_exp_f32_e32 v77, v199
	v_fma_f32 v200, v48, v200, -v174
	v_fma_f32 v201, v48, v201, -v174
	v_add_f32_e32 v219, v76, v219
	v_add_f32_e32 v220, v77, v220
	v_exp_f32_e32 v78, v200
	v_exp_f32_e32 v79, v201
	v_add_f32_e32 v219, v78, v219
	v_add_f32_e32 v220, v79, v220
	s_nop 0
	v_add_f32_e32 v157, v219, v220
	v_cvt_pk_bf16_f32 v10, v10, v11
	v_cvt_pk_bf16_f32 v11, v12, v13
	v_cvt_pk_bf16_f32 v13, v50, v51
	ds_read2_b64 v[48:51], v155 offset0:132 offset1:134
	ds_read2_b64 v[52:55], v0 offset0:164 offset1:166
	v_cvt_pk_bf16_f32 v12, v14, v15
	s_waitcnt lgkmcnt(3)
	s_nop 0
	v_mfma_f32_32x32x16_bf16 v[32:47], v[2:5], v[10:13], v[32:47]
	s_waitcnt lgkmcnt(2)
	v_mfma_f32_32x32x16_bf16 v[16:31], v[6:9], v[10:13], v[16:31]
	ds_read2_b64 v[6:9], v155 offset0:136 offset1:138
	ds_read2_b64 v[10:13], v0 offset0:168 offset1:170
	v_cvt_pk_bf16_f32 v2, v56, v57
	v_cvt_pk_bf16_f32 v3, v58, v59
	v_cvt_pk_bf16_f32 v4, v60, v61
	v_cvt_pk_bf16_f32 v5, v62, v63
	s_waitcnt lgkmcnt(3)
	s_nop 0
	v_mfma_f32_32x32x16_bf16 v[32:47], v[48:51], v[2:5], v[32:47]
	s_waitcnt lgkmcnt(2)
	v_mfma_f32_32x32x16_bf16 v[16:31], v[52:55], v[2:5], v[16:31]
	ds_read2_b64 v[48:51], v155 offset0:140 offset1:142
	ds_read2_b64 v[52:55], v0 offset0:172 offset1:174
	v_cvt_pk_bf16_f32 v2, v64, v65
	v_cvt_pk_bf16_f32 v3, v66, v67
	v_cvt_pk_bf16_f32 v4, v68, v69
	v_cvt_pk_bf16_f32 v5, v70, v71
	s_waitcnt lgkmcnt(3)
	s_nop 0
	v_mfma_f32_32x32x16_bf16 v[32:47], v[6:9], v[2:5], v[32:47]
	s_waitcnt lgkmcnt(2)
	v_mfma_f32_32x32x16_bf16 v[16:31], v[10:13], v[2:5], v[16:31]
	v_cvt_pk_bf16_f32 v2, v72, v73
	v_cvt_pk_bf16_f32 v3, v74, v75
	v_cvt_pk_bf16_f32 v4, v76, v77
	v_cvt_pk_bf16_f32 v5, v78, v79
	s_waitcnt lgkmcnt(1)
	s_nop 0
	v_mfma_f32_32x32x16_bf16 v[32:47], v[48:51], v[2:5], v[32:47]
	s_waitcnt lgkmcnt(0)
	v_mfma_f32_32x32x16_bf16 v[16:31], v[52:55], v[2:5], v[16:31]
	v_add_f32_e32 v151, v151, v157
	s_setprio 0
